# phase 3 queue: first item of each non-chain block assigned statically (item = bid-32, counter starts at gridDim-32) so the phase does not open with ~480 simultaneous pops on one atomic
# speedup vs baseline: 1.0023x; 1.0006x over previous
.LBB0_140:
	v_readlane_b32 s0, v249, 7
	s_and_b64 vcc, exec, s[12:13]
	v_readlane_b32 s1, v249, 8
	v_or_b32_e32 v234, s0, v200
	v_cmp_eq_u32_e64 s[4:5], 0, v234
	s_cbranch_vccz .LBB0_336
	s_mov_b32 s32, 1
	s_and_saveexec_b64 s[6:7], s[4:5]
	s_cbranch_execz .LBB0_143
	s_mov_b64 s[0:1], s[92:93]
	s_nop 0
	v_mov_b64_e32 v[0:1], s[0:1]
	flat_store_dword v[0:1], v197 sc1

.LBB0_172:
	s_and_saveexec_b64 s[0:1], s[44:45]
	s_xor_b64 s[4:5], exec, s[0:1]
	s_cbranch_execz .LBB0_178
	s_mov_b64 s[6:7], exec
	v_readlane_b32 s0, v248, 34
	v_readlane_b32 s1, v248, 35
	s_and_b64 s[0:1], s[6:7], s[0:1]
	s_mov_b64 exec, s[0:1]
	s_cbranch_execz .LBB0_177
	s_mov_b64 s[10:11], exec
	v_mbcnt_lo_u32_b32 v0, s10, 0
	v_mbcnt_hi_u32_b32 v0, s11, v0
	v_cmp_eq_u32_e32 vcc, 0, v0
	s_and_saveexec_b64 s[8:9], vcc
	s_cbranch_execz .LBB0_176
	s_cmp_eq_u32 s32, 1
	s_cbranch_scc0 .Lq3_atom
	v_readlane_b32 s0, v251, 5
	s_lshr_b32 s0, s0, 2
	s_sub_i32 s0, s0, 32
	s_cmp_lt_i32 s0, 0
	s_cbranch_scc1 .Lq3_atom
	v_mov_b32_e32 v1, s0
	s_branch .LBB0_176
.Lq3_atom:
	s_bcnt1_i32_b64 s0, s[10:11]
	v_mov_b32_e32 v1, s0
	global_atomic_add v1, v197, v1, s[92:93] offset:4 sc0
.LBB0_176:
	s_or_b64 exec, exec, s[8:9]
	s_mov_b32 s32, 0
	v_readlane_b32 s0, v248, 31
	s_cmp_eq_u32 s0, 12
	s_cselect_b32 s0, 0x800, 0
	s_waitcnt vmcnt(0)
	v_readfirstlane_b32 s1, v1
	s_add_i32 s0, s0, s1
	v_add_u32_e32 v0, s0, v0
	v_readlane_b32 s0, v249, 14
	s_nop 1
	v_mov_b32_e32 v1, s0
	ds_write_b32 v1, v0

.LBB0_336:
	s_and_b64 vcc, exec, s[6:7]
	v_readlane_b32 s4, v250, 43
	v_readlane_b32 s5, v250, 44
	v_readlane_b32 s6, v250, 45
	v_readlane_b32 s7, v250, 46
	v_readlane_b32 s8, v250, 47
	v_readlane_b32 s9, v250, 48
	v_readlane_b32 s10, v250, 49
	v_readlane_b32 s11, v250, 50
	s_cbranch_vccz .LBB0_409
	v_cmp_eq_u32_e32 vcc, 0, v234
	s_and_saveexec_b64 s[4:5], vcc
	s_cbranch_execz .LBB0_339
	s_mov_b64 s[0:1], s[92:93]
	s_nop 0
	v_mov_b64_e32 v[0:1], s[0:1]
	s_load_dword s0, s[54:55], 0x0
	s_waitcnt lgkmcnt(0)
	s_sub_i32 s0, s0, 32
	v_mov_b32_e32 v2, s0
	flat_store_dword v[0:1], v2 offset:4 sc1
